# NSA compressed-branch passes: tiles whose keys are all beyond the T5 far distance skip the per-element bias clamp and address arithmetic (pass 1 adds the far constant from a register, pass 2 reads the
# speedup vs baseline: 1.0222x; 1.0036x over previous
; #define LAS __attribute__((address_space(3)))
; __device__ __forceinline__ void nsa_unit(LAS unsigned char* lds, const unsigned char* hb, const bf16_t* kc, const bf16_t* vct, const float* nsg, bf16_t* omix, int b, int g, int c, int tid) {
;     const int lane = tid & 63, w = tid >> 6, r = lane & 31, h = lane >> 5;
;     const int bg = b * 2 + g, q0 = c * 64, ql = 8 * w + (r & 7), t = q0 + ql, hq = 4 * g + (r >> 3);
;     const bf16_t* Q = (const bf16_t*)(hb + HB_NSQ * MiB) + ((size_t)(b * 8 + hq) * SEQ + t) * 64;
;     LAS unsigned* selm = (LAS unsigned*)(lds + ATT_SEL); LAS float* imp = (LAS float*)(lds + ATT_X);
;     LAS const float* bt = (LAS const float*)(lds + ATT_BT) + (4 + hq) * BT_N;
;     const float* gate = nsg + ((size_t)b * SEQ + t) * 24 + hq;
;     bf16x8 qf[4]; load_q(Q, h, qf);
;     f32x16 ot[2]; zero_ot(ot);
;     LAS unsigned* oal = (LAS unsigned*)(lds + ATT_OA) + (w * 16) * 64 + lane;
;     const bf16_t* Kc = kc + (size_t)bg * 512 * 64; const bf16_t* Vc = vct + (size_t)bg * 64 * 512;
;     const int ntc = (4 * c + 3 + 63) >> 6;
;     float lsum = 0.f;
;     TILE_LOOP(Kc, Vc, 512, 0, ntc, {
.LBB0_929:
	s_lshl_b32 s4, s14, 2
	v_and_b32_e32 v142, 31, v130
	s_addk_i32 s4, 0x42
	v_lshl_add_u64 v[118:119], s[10:11], 0, v[134:135]
	v_lshl_add_u64 v[0:1], s[76:77], 0, v[0:1]
	v_lshlrev_b32_e32 v116, 4, v140
	v_mov_b32_e32 v117, v81
	v_readlane_b32 s10, v255, 31
	v_mul_u32_u24_e32 v4, 0x480, v153
	s_lshr_b32 s17, s4, 6
	v_lshlrev_b32_e32 v5, 1, v142
	v_lshrrev_b32_e32 v6, 1, v130
	v_lshl_add_u64 v[0:1], v[0:1], 0, v[116:117]
	v_readlane_b32 s11, v255, 32
	v_add_u32_e32 v117, v2, v140
	s_lshl_b32 s4, s15, 6
	v_lshlrev_b32_e32 v152, 3, v3
	v_add_u32_e32 v211, 0x100, v4
	ds_read_b32 v234, v211 offset:42620
	v_and_b32_e32 v4, 19, v130
	v_and_b32_e32 v5, 8, v5
	v_and_b32_e32 v6, 4, v6
	v_lshlrev_b32_e32 v3, 7, v3
	v_lshl_add_u64 v[120:121], s[10:11], 0, v[0:1]
	v_subrev_u32_e32 v0, s4, v117
	v_or3_b32 v4, v6, v4, v5
	v_add_u32_e32 v214, 0x80, v136
	v_sub_u32_e32 v143, v0, v3
	v_mov_b32_e32 v135, 0
	v_and_b32_e32 v144, 63, v130
	s_mov_b32 s13, 1
	v_mul_u32_u24_e32 v212, 0x90, v4
	v_mul_u32_u24_e32 v213, 0x90, v142
	v_add_u32_e32 v80, 0x1fa1, v143
	s_sub_i32 s18, 0, s17
	v_mov_b64_e32 v[132:133], v[120:121]
	v_mov_b32_e32 v138, v214
	v_mov_b32_e32 v0, 0
	v_mov_b32_e32 v1, v135
	v_mov_b32_e32 v2, v135
	v_mov_b32_e32 v3, v135
	v_mov_b32_e32 v4, v135
	v_mov_b32_e32 v5, v135
	v_mov_b32_e32 v6, v135
	v_mov_b32_e32 v7, v135
	v_mov_b32_e32 v8, v135
	v_mov_b32_e32 v9, v135
	v_mov_b32_e32 v10, v135
	v_mov_b32_e32 v11, v135
	v_mov_b32_e32 v12, v135
	v_mov_b32_e32 v13, v135
	v_mov_b32_e32 v14, v135
	v_mov_b32_e32 v15, v135
	v_mov_b32_e32 v16, 0
	v_mov_b32_e32 v17, v135
	v_mov_b32_e32 v18, v135
	v_mov_b32_e32 v19, v135
	v_mov_b32_e32 v20, v135
	v_mov_b32_e32 v21, v135
	v_mov_b32_e32 v22, v135
	v_mov_b32_e32 v23, v135
	v_mov_b32_e32 v24, v135
	v_mov_b32_e32 v25, v135
	v_mov_b32_e32 v26, v135
	v_mov_b32_e32 v27, v135
	v_mov_b32_e32 v28, v135
	v_mov_b32_e32 v29, v135
	v_mov_b32_e32 v30, v135
	v_mov_b32_e32 v31, v135
	s_waitcnt lgkmcnt(0)
	s_barrier
	s_add_i32 s10, s13, 1
	s_cmp_ge_u32 s10, s17
	s_cbranch_scc1 .LBB0_931

; #define LAS __attribute__((address_space(3)))
; __device__ __forceinline__ float ex2(float x) { return __builtin_amdgcn_exp2f(x); }
; #define MFMA32(a, b, c) __builtin_amdgcn_mfma_f32_32x32x16_bf16((a), (b), (c), 0, 0, 0)
; template <int MODE> __device__ __forceinline__ void soft_sub(f32x16& st, float& lsum, bool lane_valid, int dist0, int dmax, LAS const float* bt) {
;     ...
;         float bb[16];
; #pragma unroll
;         for (int i = 0; i < 16; ++i) { int d = dist0 - 16 * (16 * (i >> 3) + (i & 7)); d = d < -64 ? -64 : (d > 223 ? 223 : d); bb[i] = bt[d + 64]; }
; #pragma unroll
;         for (int i = 0; i < 16; ++i) { const float p = ex2(st[i] + bb[i]); lsum += p; st[i] = p; }
; template <int MODE> __device__ __forceinline__ void tile_soft_gen(LAS const unsigned char* ks, LAS const unsigned char* vs, const bf16x8 (&qf)[4], f32x16 (&ot)[2], float& lsum, ...
;     const float init = MODE == 0 ? (lane_valid ? bt[BT_FAR] : -3.0e38f) : 0.f;
;     const int pr = (r & 0x13) | ((r & 4) << 1) | ((r & 8) >> 1);
;     LAS const unsigned char* kp = ks + pr * 144 + h * 16; LAS const unsigned char* vp = vs + r * 144 + h * 16;
;     bf16x8 k0[4], k1[4], v0[2][2], v1[2][2];
; #pragma unroll
;     for (int kk = 0; kk < 4; ++kk) { k0[kk] = *(LAS const bf16x8*)(kp + kk * 32); k1[kk] = *(LAS const bf16x8*)(kp + 32 * 144 + kk * 32); }
;     __builtin_amdgcn_sched_barrier(0);
;     f32x16 s0, s1;
; #pragma unroll
;     for (int i = 0; i < 16; ++i) { s0[i] = init; s1[i] = init; }
; #pragma unroll
;     for (int kk = 0; kk < 4; ++kk) s0 = MFMA32(k0[kk], qf[kk], s0);
; #pragma unroll
;     for (int mt = 0; mt < 2; ++mt)
; #pragma unroll
;         for (int j = 0; j < 2; ++j) v0[mt][j] = *(LAS const bf16x8*)(vp + 32 * mt * 144 + 32 * j);
;     __builtin_amdgcn_sched_barrier(0);
; #pragma unroll
;     for (int kk = 0; kk < 4; ++kk) s1 = MFMA32(k1[kk], qf[kk], s1);
; #pragma unroll
;     for (int mt = 0; mt < 2; ++mt)
; #pragma unroll
;         for (int j = 0; j < 2; ++j) v1[mt][j] = *(LAS const bf16x8*)(vp + 32 * mt * 144 + 64 + 32 * j);
;     soft_sub<MODE>(s0, lsum, lane_valid, dist00, dmax, bt);
.LBB0_931:
	v_cmp_gt_i32_e32 vcc, 0x3f0, v80
	s_cbranch_vccz .Lp1_far
	s_add_i32 s11, s13, -1
	s_and_b32 s11, s11, 1
	s_mul_i32 s19, s11, 0x4800
	s_addk_i32 s19, 0x100
	v_add3_u32 v48, s19, v212, v154
	ds_read_b128 v[32:35], v48
	ds_read_b128 v[36:39], v48 offset:32
	ds_read_b128 v[40:43], v48 offset:4608
	ds_read_b128 v[98:101], v48 offset:4640
	ds_read_b128 v[44:47], v48 offset:64
	ds_read_b128 v[156:159], v48 offset:96
	ds_read_b128 v[102:105], v48 offset:4672
	ds_read_b128 v[106:109], v48 offset:4704
	s_waitcnt lgkmcnt(7)
	v_mfma_f32_32x32x16_bf16 v[48:63], v[32:35], v[82:85], 0
	v_add3_u32 v139, s19, v213, v154
	ds_read_b128 v[160:163], v139 offset:9216
	ds_read_b128 v[170:173], v139 offset:9248
	ds_read_b128 v[174:177], v139 offset:13824
	ds_read_b128 v[216:219], v139 offset:13856
	s_waitcnt lgkmcnt(10)
	v_mfma_f32_32x32x16_bf16 v[48:63], v[36:39], v[86:89], v[48:63]
	s_waitcnt lgkmcnt(7)
	v_mfma_f32_32x32x16_bf16 v[48:63], v[44:47], v[90:93], v[48:63]
	v_mfma_f32_32x32x16_bf16 v[32:47], v[40:43], v[82:85], 0
	v_med3_i32 v145, v80, s88, v193
	v_med3_i32 v178, v80, 32, v200
	v_med3_i32 v179, v80, 48, v201
	v_med3_i32 v180, v80, s91, v202
	v_med3_i32 v181, v80, s89, v203
	v_med3_i32 v182, v80, s94, v204
	v_med3_i32 v183, v80, s95, v205
	v_mfma_f32_32x32x16_bf16 v[32:47], v[98:101], v[86:89], v[32:47]
	v_med3_i32 v184, v80, s33, v206
	v_med3_i32 v185, v80, s92, v207
	v_med3_i32 v186, v80, s93, v208
	v_med3_i32 v187, v80, s84, v209
	v_lshl_add_u32 v145, v145, 2, v211
	v_lshl_add_u32 v178, v178, 2, v211
	v_lshl_add_u32 v179, v179, 2, v211
	s_waitcnt lgkmcnt(5)
	v_mfma_f32_32x32x16_bf16 v[32:47], v[102:105], v[90:93], v[32:47]
	v_lshl_add_u32 v180, v180, 2, v211
	v_lshl_add_u32 v181, v181, 2, v211
	v_lshl_add_u32 v182, v182, 2, v211
	v_lshl_add_u32 v183, v183, 2, v211
	v_lshl_add_u32 v184, v184, 2, v211
	v_lshl_add_u32 v185, v185, 2, v211
	v_lshl_add_u32 v186, v186, 2, v211
	v_mfma_f32_32x32x16_bf16 v[48:63], v[156:159], v[94:97], v[48:63]
	v_med3_i32 v156, v80, s97, v194
	v_med3_i32 v157, v80, -16, v197
	v_med3_i32 v158, v80, 0, v198
	v_med3_i32 v159, v80, 16, v199
	v_lshl_add_u32 v156, v156, 2, v211
	v_lshl_add_u32 v157, v157, 2, v211
	v_lshl_add_u32 v158, v158, 2, v211
	s_waitcnt lgkmcnt(4)
	v_mfma_f32_32x32x16_bf16 v[32:47], v[106:109], v[94:97], v[32:47]
	ds_read_b128 v[106:109], v139 offset:9280
	ds_read_b128 v[102:105], v139 offset:9312
	ds_read_b128 v[110:113], v139 offset:13888
	ds_read_b128 v[98:101], v139 offset:13920
	v_med3_i32 v139, v80, s75, v192
	v_lshl_add_u32 v139, v139, 2, v211
	v_lshl_add_u32 v159, v159, 2, v211
	v_lshl_add_u32 v187, v187, 2, v211
	ds_read_b32 v139, v139 offset:41728
	ds_read_b32 v145, v145 offset:41664
	ds_read_b32 v156, v156 offset:41600
	ds_read_b32 v157, v157 offset:41536
	ds_read_b32 v158, v158 offset:41472
	ds_read_b32 v159, v159 offset:41408
	ds_read_b32 v178, v178 offset:41344
	ds_read_b32 v179, v179 offset:41280
	ds_read_b32 v180, v180 offset:40704
	ds_read_b32 v181, v181 offset:40640
	ds_read_b32 v182, v182 offset:40576
	ds_read_b32 v183, v183 offset:40512
	ds_read_b32 v184, v184 offset:40448
	ds_read_b32 v185, v185 offset:40384
	ds_read_b32 v186, v186 offset:40320
	ds_read_b32 v187, v187 offset:40256
	s_waitcnt lgkmcnt(14)
	v_add_f32_e32 v48, v48, v139
	v_add_f32_e32 v49, v49, v145
	s_waitcnt lgkmcnt(13)
	v_add_f32_e32 v50, v50, v156
	s_waitcnt lgkmcnt(12)
	v_add_f32_e32 v51, v51, v157
	s_waitcnt lgkmcnt(11)
	v_add_f32_e32 v52, v52, v158
	s_waitcnt lgkmcnt(10)
	v_add_f32_e32 v53, v53, v159
	s_waitcnt lgkmcnt(9)
	v_add_f32_e32 v54, v54, v178
	s_waitcnt lgkmcnt(8)
	v_add_f32_e32 v55, v55, v179
	s_waitcnt lgkmcnt(7)
	v_add_f32_e32 v56, v56, v180
	s_waitcnt lgkmcnt(6)
	v_add_f32_e32 v57, v57, v181
	s_waitcnt lgkmcnt(5)
	v_add_f32_e32 v58, v58, v182
	s_waitcnt lgkmcnt(4)
	v_add_f32_e32 v59, v59, v183
	s_waitcnt lgkmcnt(3)
	v_add_f32_e32 v60, v60, v184
	s_waitcnt lgkmcnt(2)
	v_add_f32_e32 v61, v61, v185
	s_waitcnt lgkmcnt(1)
	v_add_f32_e32 v62, v62, v186
	s_waitcnt lgkmcnt(0)
; #define MFMA32(a, b, c) __builtin_amdgcn_mfma_f32_32x32x16_bf16((a), (b), (c), 0, 0, 0)
; template <int MODE> __device__ __forceinline__ void tile_soft_gen(LAS const unsigned char* ks, LAS const unsigned char* vs, const bf16x8 (&qf)[4], f32x16 (&ot)[2], float& lsum, ...
;     ...
;     soft_sub<MODE>(s0, lsum, lane_valid, dist00, dmax, bt);
;     __builtin_amdgcn_sched_barrier(0);
; #pragma unroll
;     for (int j = 0; j < 2; ++j) { const bf16x8 pf = pack_p(s0, j); ot[0] = MFMA32(v0[0][j], pf, ot[0]); ot[1] = MFMA32(v0[1][j], pf, ot[1]); }
;     soft_sub<MODE>(s1, lsum, lane_valid, dist00 - (MODE == 3 ? 512 : 32), dmax, bt);
;     __builtin_amdgcn_sched_barrier(0);
; #pragma unroll
;     for (int j = 0; j < 2; ++j) { const bf16x8 pf = pack_p(s1, j); ot[0] = MFMA32(v1[0][j], pf, ot[0]); ot[1] = MFMA32(v1[1][j], pf, ot[1]); }
	v_add_f32_e32 v63, v63, v187
	v_exp_f32_e32 v48, v48
	v_exp_f32_e32 v49, v49
	v_exp_f32_e32 v50, v50
	v_exp_f32_e32 v51, v51
	v_exp_f32_e32 v52, v52
	v_exp_f32_e32 v53, v53
	v_exp_f32_e32 v54, v54
	v_exp_f32_e32 v55, v55
	v_exp_f32_e32 v56, v56
	v_exp_f32_e32 v57, v57
	v_exp_f32_e32 v58, v58
	v_exp_f32_e32 v59, v59
	v_exp_f32_e32 v60, v60
	v_exp_f32_e32 v61, v61
	v_exp_f32_e32 v62, v62
	v_exp_f32_e32 v63, v63
	v_cvt_pk_bf16_f32 v156, v48, v49
	v_cvt_pk_bf16_f32 v157, v50, v51
	v_cvt_pk_bf16_f32 v158, v52, v53
	v_cvt_pk_bf16_f32 v159, v54, v55
	v_add_u32_e32 v139, 0xfffffe00, v80
	v_med3_i32 v145, v139, s75, v192
	v_mfma_f32_32x32x16_bf16 v[0:15], v[160:163], v[156:159], v[0:15]
	v_med3_i32 v160, v139, 16, v199
	v_med3_i32 v161, v139, 32, v200
	v_med3_i32 v162, v139, 48, v201
	v_med3_i32 v163, v139, s91, v202
	v_lshl_add_u32 v145, v145, 2, v211
	v_lshl_add_u32 v160, v160, 2, v211
	v_lshl_add_u32 v161, v161, 2, v211
	v_mfma_f32_32x32x16_bf16 v[16:31], v[174:177], v[156:159], v[16:31]
	v_cvt_pk_bf16_f32 v156, v56, v57
	v_cvt_pk_bf16_f32 v157, v58, v59
	v_cvt_pk_bf16_f32 v158, v60, v61
	v_cvt_pk_bf16_f32 v159, v62, v63
	v_med3_i32 v174, v139, s92, v207
	v_med3_i32 v175, v139, s93, v208
	v_lshl_add_u32 v162, v162, 2, v211
	v_mfma_f32_32x32x16_bf16 v[0:15], v[170:173], v[156:159], v[0:15]
	v_med3_i32 v170, v139, s89, v203
	v_med3_i32 v171, v139, s94, v204
	v_med3_i32 v172, v139, s95, v205
	v_med3_i32 v173, v139, s33, v206
	v_lshl_add_u32 v163, v163, 2, v211
	v_lshl_add_u32 v170, v170, 2, v211
	v_lshl_add_u32 v171, v171, 2, v211
	v_mfma_f32_32x32x16_bf16 v[16:31], v[216:219], v[156:159], v[16:31]
	v_med3_i32 v156, v139, s88, v193
	v_med3_i32 v157, v139, s97, v194
	v_med3_i32 v158, v139, -16, v197
	v_med3_i32 v159, v139, 0, v198
	v_med3_i32 v139, v139, s84, v209
	v_lshl_add_u32 v156, v156, 2, v211
	v_lshl_add_u32 v157, v157, 2, v211
	v_lshl_add_u32 v158, v158, 2, v211
	v_lshl_add_u32 v159, v159, 2, v211
	v_lshl_add_u32 v172, v172, 2, v211
	v_lshl_add_u32 v173, v173, 2, v211
	v_lshl_add_u32 v174, v174, 2, v211
	v_lshl_add_u32 v175, v175, 2, v211
	v_lshl_add_u32 v139, v139, 2, v211
	ds_read_b32 v145, v145 offset:41728
	ds_read_b32 v156, v156 offset:41664
	ds_read_b32 v157, v157 offset:41600
	ds_read_b32 v158, v158 offset:41536
	ds_read_b32 v159, v159 offset:41472
	ds_read_b32 v160, v160 offset:41408
	ds_read_b32 v161, v161 offset:41344
	ds_read_b32 v139, v139 offset:40256
	ds_read_b32 v162, v162 offset:41280
	ds_read_b32 v163, v163 offset:40704
	ds_read_b32 v170, v170 offset:40640
	ds_read_b32 v171, v171 offset:40576
	ds_read_b32 v172, v172 offset:40512
	ds_read_b32 v173, v173 offset:40448
	ds_read_b32 v174, v174 offset:40384
	ds_read_b32 v175, v175 offset:40320
	s_waitcnt lgkmcnt(14)
	v_add_f32_e32 v32, v32, v145
	v_add_f32_e32 v33, v33, v156
	s_waitcnt lgkmcnt(13)
	v_add_f32_e32 v34, v34, v157
	s_waitcnt lgkmcnt(12)
	v_add_f32_e32 v35, v35, v158
	s_waitcnt lgkmcnt(11)
	v_add_f32_e32 v36, v36, v159
	s_waitcnt lgkmcnt(10)
	v_add_f32_e32 v37, v37, v160
	s_waitcnt lgkmcnt(9)
	v_add_f32_e32 v38, v38, v161
	s_waitcnt lgkmcnt(7)
	v_add_f32_e32 v39, v39, v162
	s_waitcnt lgkmcnt(6)
	v_add_f32_e32 v40, v40, v163
	s_waitcnt lgkmcnt(5)
	v_add_f32_e32 v41, v41, v170
	s_waitcnt lgkmcnt(4)
	v_add_f32_e32 v42, v42, v171
	s_waitcnt lgkmcnt(3)
	v_add_f32_e32 v43, v43, v172
	s_waitcnt lgkmcnt(2)
	v_add_f32_e32 v44, v44, v173
	s_waitcnt lgkmcnt(1)
	v_add_f32_e32 v45, v45, v174
	s_waitcnt lgkmcnt(0)
	v_add_f32_e32 v46, v46, v175
	v_add_f32_e32 v47, v47, v139
	v_exp_f32_e32 v32, v32
	v_exp_f32_e32 v33, v33
	v_exp_f32_e32 v34, v34
	v_exp_f32_e32 v35, v35
	v_exp_f32_e32 v36, v36
	v_exp_f32_e32 v37, v37
	v_exp_f32_e32 v38, v38
	v_exp_f32_e32 v39, v39
	v_exp_f32_e32 v40, v40
	v_exp_f32_e32 v41, v41
	v_exp_f32_e32 v42, v42
	v_exp_f32_e32 v43, v43
	v_exp_f32_e32 v44, v44
	v_exp_f32_e32 v45, v45
	v_exp_f32_e32 v46, v46
	v_exp_f32_e32 v47, v47
	v_cvt_pk_bf16_f32 v156, v32, v33
	v_cvt_pk_bf16_f32 v157, v34, v35
	v_cvt_pk_bf16_f32 v158, v36, v37
	v_cvt_pk_bf16_f32 v159, v38, v39
	s_cmp_ge_u32 s13, s17
	s_nop 0
	v_mfma_f32_32x32x16_bf16 v[0:15], v[106:109], v[156:159], v[0:15]
	v_cvt_pk_bf16_f32 v106, v40, v41
	v_cvt_pk_bf16_f32 v107, v42, v43
	v_cvt_pk_bf16_f32 v108, v44, v45
	v_cvt_pk_bf16_f32 v109, v46, v47
	v_mfma_f32_32x32x16_bf16 v[16:31], v[110:113], v[156:159], v[16:31]
	s_nop 0
	v_mfma_f32_32x32x16_bf16 v[0:15], v[102:105], v[106:109], v[0:15]
	v_mfma_f32_32x32x16_bf16 v[16:31], v[98:101], v[106:109], v[16:31]
.Lp1_join:
	s_cbranch_scc1 .LBB0_933
	s_xor_b32 s11, s11, 1
	s_mulk_i32 s11, 0x4800
	v_add_u32_e32 v98, s11, v155
	s_waitcnt vmcnt(1)
	ds_write_b128 v98, v[76:79]
	s_waitcnt vmcnt(0)
	ds_write_b128 v98, v[72:75] offset:9216

; #define LAS __attribute__((address_space(3)))
; #define MFMA32(a, b, c) __builtin_amdgcn_mfma_f32_32x32x16_bf16((a), (b), (c), 0, 0, 0)
; template <int MODE> __device__ __forceinline__ void tile_soft_gen(LAS const unsigned char* ks, LAS const unsigned char* vs, const bf16x8 (&qf)[4], f32x16 (&ot)[2], float& lsum, ...
;     const float init = MODE == 0 ? (lane_valid ? bt[BT_FAR] : -3.0e38f) : 0.f;
;     const int pr = (r & 0x13) | ((r & 4) << 1) | ((r & 8) >> 1);
;     LAS const unsigned char* kp = ks + pr * 144 + h * 16; LAS const unsigned char* vp = vs + r * 144 + h * 16;
;     bf16x8 k0[4], k1[4], v0[2][2], v1[2][2];
; #pragma unroll
;     for (int kk = 0; kk < 4; ++kk) { k0[kk] = *(LAS const bf16x8*)(kp + kk * 32); k1[kk] = *(LAS const bf16x8*)(kp + 32 * 144 + kk * 32); }
;     __builtin_amdgcn_sched_barrier(0);
;     f32x16 s0, s1;
; #pragma unroll
;     for (int i = 0; i < 16; ++i) { s0[i] = init; s1[i] = init; }
; #pragma unroll
;     for (int kk = 0; kk < 4; ++kk) s0 = MFMA32(k0[kk], qf[kk], s0);
; #pragma unroll
;     for (int mt = 0; mt < 2; ++mt)
; #pragma unroll
;         for (int j = 0; j < 2; ++j) v0[mt][j] = *(LAS const bf16x8*)(vp + 32 * mt * 144 + 32 * j);
;     __builtin_amdgcn_sched_barrier(0);
; #pragma unroll
;     for (int kk = 0; kk < 4; ++kk) s1 = MFMA32(k1[kk], qf[kk], s1);
; #pragma unroll
;     for (int mt = 0; mt < 2; ++mt)
; #pragma unroll
;         for (int j = 0; j < 2; ++j) v1[mt][j] = *(LAS const bf16x8*)(vp + 32 * mt * 144 + 64 + 32 * j);
;     soft_sub<MODE>(s0, lsum, lane_valid, dist00, dmax, bt);
;     __builtin_amdgcn_sched_barrier(0);
; #pragma unroll
;     for (int j = 0; j < 2; ++j) { const bf16x8 pf = pack_p(s0, j); ot[0] = MFMA32(v0[0][j], pf, ot[0]); ot[1] = MFMA32(v0[1][j], pf, ot[1]); }
;     soft_sub<MODE>(s1, lsum, lane_valid, dist00 - (MODE == 3 ? 512 : 32), dmax, bt);
;     __builtin_amdgcn_sched_barrier(0);
; #pragma unroll
;     for (int j = 0; j < 2; ++j) { const bf16x8 pf = pack_p(s1, j); ot[0] = MFMA32(v1[0][j], pf, ot[0]); ot[1] = MFMA32(v1[1][j], pf, ot[1]); }
.Lp1_far:
	s_add_i32 s11, s13, -1
	s_and_b32 s11, s11, 1
	s_mul_i32 s19, s11, 0x4800
	s_addk_i32 s19, 0x100
	v_add3_u32 v48, s19, v212, v154
	ds_read_b128 v[32:35], v48
	ds_read_b128 v[36:39], v48 offset:32
	ds_read_b128 v[40:43], v48 offset:4608
	ds_read_b128 v[98:101], v48 offset:4640
	ds_read_b128 v[44:47], v48 offset:64
	ds_read_b128 v[156:159], v48 offset:96
	ds_read_b128 v[102:105], v48 offset:4672
	ds_read_b128 v[106:109], v48 offset:4704
	s_waitcnt lgkmcnt(7)
	v_mfma_f32_32x32x16_bf16 v[48:63], v[32:35], v[82:85], 0
	v_add3_u32 v139, s19, v213, v154
	ds_read_b128 v[160:163], v139 offset:9216
	ds_read_b128 v[170:173], v139 offset:9248
	ds_read_b128 v[174:177], v139 offset:13824
	ds_read_b128 v[216:219], v139 offset:13856
	s_waitcnt lgkmcnt(10)
	v_mfma_f32_32x32x16_bf16 v[48:63], v[36:39], v[86:89], v[48:63]
	s_waitcnt lgkmcnt(7)
	v_mfma_f32_32x32x16_bf16 v[48:63], v[44:47], v[90:93], v[48:63]
	v_mfma_f32_32x32x16_bf16 v[32:47], v[40:43], v[82:85], 0
	v_mfma_f32_32x32x16_bf16 v[32:47], v[98:101], v[86:89], v[32:47]
	s_waitcnt lgkmcnt(5)
	v_mfma_f32_32x32x16_bf16 v[32:47], v[102:105], v[90:93], v[32:47]
	v_mfma_f32_32x32x16_bf16 v[48:63], v[156:159], v[94:97], v[48:63]
	s_waitcnt lgkmcnt(4)
	v_mfma_f32_32x32x16_bf16 v[32:47], v[106:109], v[94:97], v[32:47]
	ds_read_b128 v[106:109], v139 offset:9280
	ds_read_b128 v[102:105], v139 offset:9312
	ds_read_b128 v[110:113], v139 offset:13888
	ds_read_b128 v[98:101], v139 offset:13920
	s_nop 5
	v_add_f32_e32 v48, v48, v234
	v_add_f32_e32 v49, v49, v234
	v_add_f32_e32 v50, v50, v234
	v_add_f32_e32 v51, v51, v234
	v_add_f32_e32 v52, v52, v234
	v_add_f32_e32 v53, v53, v234
	v_add_f32_e32 v54, v54, v234
	v_add_f32_e32 v55, v55, v234
	v_add_f32_e32 v56, v56, v234
	v_add_f32_e32 v57, v57, v234
	v_add_f32_e32 v58, v58, v234
	v_add_f32_e32 v59, v59, v234
	v_add_f32_e32 v60, v60, v234
	v_add_f32_e32 v61, v61, v234
	v_add_f32_e32 v62, v62, v234
	v_add_f32_e32 v63, v63, v234
	v_exp_f32_e32 v48, v48
	v_exp_f32_e32 v49, v49
	v_exp_f32_e32 v50, v50
	v_exp_f32_e32 v51, v51
	v_exp_f32_e32 v52, v52
	v_exp_f32_e32 v53, v53
	v_exp_f32_e32 v54, v54
	v_exp_f32_e32 v55, v55
	v_exp_f32_e32 v56, v56
	v_exp_f32_e32 v57, v57
	v_exp_f32_e32 v58, v58
	v_exp_f32_e32 v59, v59
	v_exp_f32_e32 v60, v60
	v_exp_f32_e32 v61, v61
	v_exp_f32_e32 v62, v62
	v_exp_f32_e32 v63, v63
	v_cvt_pk_bf16_f32 v156, v48, v49
	v_cvt_pk_bf16_f32 v157, v50, v51
	v_cvt_pk_bf16_f32 v158, v52, v53
	v_cvt_pk_bf16_f32 v159, v54, v55
	s_waitcnt lgkmcnt(7)
	s_nop 0
	v_mfma_f32_32x32x16_bf16 v[0:15], v[160:163], v[156:159], v[0:15]
	s_waitcnt lgkmcnt(5)
	v_mfma_f32_32x32x16_bf16 v[16:31], v[174:177], v[156:159], v[16:31]
	v_cvt_pk_bf16_f32 v156, v56, v57
	v_cvt_pk_bf16_f32 v157, v58, v59
	v_cvt_pk_bf16_f32 v158, v60, v61
	v_cvt_pk_bf16_f32 v159, v62, v63
	s_nop 1
	v_mfma_f32_32x32x16_bf16 v[0:15], v[170:173], v[156:159], v[0:15]
	s_waitcnt lgkmcnt(4)
	v_mfma_f32_32x32x16_bf16 v[16:31], v[216:219], v[156:159], v[16:31]
	v_add_f32_e32 v32, v32, v234
	v_add_f32_e32 v33, v33, v234
	v_add_f32_e32 v34, v34, v234
	v_add_f32_e32 v35, v35, v234
	v_add_f32_e32 v36, v36, v234
	v_add_f32_e32 v37, v37, v234
	v_add_f32_e32 v38, v38, v234
	v_add_f32_e32 v39, v39, v234
	v_add_f32_e32 v40, v40, v234
	v_add_f32_e32 v41, v41, v234
	v_add_f32_e32 v42, v42, v234
	v_add_f32_e32 v43, v43, v234
	v_add_f32_e32 v44, v44, v234
	v_add_f32_e32 v45, v45, v234
	v_add_f32_e32 v46, v46, v234
	v_add_f32_e32 v47, v47, v234
	v_exp_f32_e32 v32, v32
	v_exp_f32_e32 v33, v33
	v_exp_f32_e32 v34, v34
	v_exp_f32_e32 v35, v35
	v_exp_f32_e32 v36, v36
	v_exp_f32_e32 v37, v37
	v_exp_f32_e32 v38, v38
	v_exp_f32_e32 v39, v39
	v_exp_f32_e32 v40, v40
	v_exp_f32_e32 v41, v41
	v_exp_f32_e32 v42, v42
	v_exp_f32_e32 v43, v43
	v_exp_f32_e32 v44, v44
	v_exp_f32_e32 v45, v45
	v_exp_f32_e32 v46, v46
	v_exp_f32_e32 v47, v47
	v_cvt_pk_bf16_f32 v156, v32, v33
	v_cvt_pk_bf16_f32 v157, v34, v35
	v_cvt_pk_bf16_f32 v158, v36, v37
	v_cvt_pk_bf16_f32 v159, v38, v39
	s_cmp_ge_u32 s13, s17
	s_nop 0
	s_waitcnt lgkmcnt(3)
	v_mfma_f32_32x32x16_bf16 v[0:15], v[106:109], v[156:159], v[0:15]
	v_cvt_pk_bf16_f32 v106, v40, v41
	v_cvt_pk_bf16_f32 v107, v42, v43
	v_cvt_pk_bf16_f32 v108, v44, v45
	v_cvt_pk_bf16_f32 v109, v46, v47
	s_waitcnt lgkmcnt(1)
	v_mfma_f32_32x32x16_bf16 v[16:31], v[110:113], v[156:159], v[16:31]
	s_nop 0
	v_mfma_f32_32x32x16_bf16 v[0:15], v[102:105], v[106:109], v[0:15]
	s_waitcnt lgkmcnt(0)
	v_mfma_f32_32x32x16_bf16 v[16:31], v[98:101], v[106:109], v[16:31]
	s_branch .Lp1_join

; #define LAS __attribute__((address_space(3)))
; __device__ __forceinline__ void imp_sub(f32x16& st, float invc, int nbase, LAS float* improw, int r) {
; #pragma unroll
;     for (int j = 0; j < 2; ++j) { const int a = (nbase + 16 * j) >> 3;
;         float s0 = ((st[8 * j] + st[8 * j + 1]) + (st[8 * j + 2] + st[8 * j + 3])) * invc;
;         float s1 = ((st[8 * j + 3] + st[8 * j + 4]) + (st[8 * j + 5] + st[8 * j + 6]) + st[8 * j + 7]) * invc;
;         float s2 = st[8 * j + 7] * invc;
;         s0 += __shfl_xor(s0, 8); s0 += __shfl_xor(s0, 16); s1 += __shfl_xor(s1, 8); s1 += __shfl_xor(s1, 16); s2 += __shfl_xor(s2, 8); s2 += __shfl_xor(s2, 16);
;         if (r < 8) { LAS float* ip = improw + 2 * a; ip[0] += s0; ip[1] += s1; if (2 * a + 2 < 128) ip[2] += s2; } }
; __device__ __forceinline__ void nsa_unit(LAS unsigned char* lds, const unsigned char* hb, const bf16_t* kc, const bf16_t* vct, const float* nsg, bf16_t* omix, int b, int g, int c, int tid) {
;     ...
;     TILE_LOOP(Kc, Vc, 512, 0, ntc, {
;         f32x16 s0 = qk_sub(ks, 0, qf, r, h); f32x16 s1 = qk_sub(ks, 1, qf, r, h); float dummy = 0.f;
;         const int dist00 = t - 31 - 16 * (key0 + 8 * h);
;         soft_sub<3>(s0, dummy, true, dist00, 0, bt); imp_sub(s0, invc, key0 + 8 * h, imp + ql * 129, r);
;         soft_sub<3>(s1, dummy, true, dist00 - 512, 0, bt); imp_sub(s1, invc, key0 + 32 + 8 * h, imp + ql * 129, r); });
.LBB0_946:
	v_mov_b32_e32 v238, 0x1f0
	v_cmp_gt_i32_e64 s[98:99], v238, v55
	s_cmp_eq_u64 s[98:99], 0
	s_cbranch_scc1 .Lp2_far
	s_add_i32 s6, s13, -1
	s_and_b32 s20, s6, 1
	s_mul_i32 s6, s20, 0x4800
	v_add_u32_e32 v60, s6, v53
	ds_read_b128 v[0:3], v60
	ds_read_b128 v[4:7], v60 offset:32
	v_add_u32_e32 v64, 0x200, v55
	v_med3_i32 v63, v64, s93, v208
	v_lshl_add_u32 v63, v63, 2, v211
	s_waitcnt lgkmcnt(1)
	v_mfma_f32_32x32x16_bf16 v[16:31], v[0:3], v[82:85], 0
	ds_read_b128 v[0:3], v60 offset:64
	ds_read_b128 v[56:59], v60 offset:4640
	v_med3_i32 v62, v64, s92, v207
	v_lshl_add_u32 v62, v62, 2, v211
	v_med3_i32 v61, v64, s33, v206
	v_lshl_add_u32 v61, v61, 2, v211
	ds_read_b32 v63, v63 offset:40320
	s_waitcnt lgkmcnt(3)
	v_mfma_f32_32x32x16_bf16 v[16:31], v[4:7], v[86:89], v[16:31]
	ds_read_b32 v62, v62 offset:40384
	ds_read_b32 v61, v61 offset:40448
	s_waitcnt lgkmcnt(4)
	v_mfma_f32_32x32x16_bf16 v[16:31], v[0:3], v[90:93], v[16:31]
	ds_read_b128 v[0:3], v60 offset:96
	s_waitcnt lgkmcnt(0)
	v_mfma_f32_32x32x16_bf16 v[16:31], v[0:3], v[94:97], v[16:31]
	ds_read_b128 v[0:3], v60 offset:4608
	s_waitcnt lgkmcnt(0)
	v_mfma_f32_32x32x16_bf16 v[0:15], v[0:3], v[82:85], 0
	v_mfma_f32_32x32x16_bf16 v[0:15], v[56:59], v[86:89], v[0:15]
	ds_read_b128 v[56:59], v60 offset:4672
	s_waitcnt lgkmcnt(0)
	v_mfma_f32_32x32x16_bf16 v[0:15], v[56:59], v[90:93], v[0:15]
	ds_read_b128 v[56:59], v60 offset:4704
	v_med3_i32 v60, v64, s95, v205
	v_lshl_add_u32 v60, v60, 2, v211
	ds_read_b32 v60, v60 offset:40512
	s_waitcnt lgkmcnt(1)
	v_mfma_f32_32x32x16_bf16 v[0:15], v[56:59], v[94:97], v[0:15]
	v_med3_i32 v57, v64, s75, v192
	v_lshl_add_u32 v57, v57, 2, v211
	ds_read_b32 v65, v57 offset:41728
	v_med3_i32 v57, v64, s88, v193
	v_lshl_add_u32 v57, v57, 2, v211
	ds_read_b32 v66, v57 offset:41664
	v_med3_i32 v57, v64, s97, v194
	v_lshl_add_u32 v57, v57, 2, v211
	ds_read_b32 v67, v57 offset:41600
	v_med3_i32 v57, v64, -16, v197
	v_lshl_add_u32 v57, v57, 2, v211
	ds_read_b32 v68, v57 offset:41536
	v_med3_i32 v57, v64, 0, v198
	v_lshl_add_u32 v57, v57, 2, v211
	ds_read_b32 v69, v57 offset:41472
	v_med3_i32 v57, v64, 16, v199
	v_lshl_add_u32 v57, v57, 2, v211
	ds_read_b32 v70, v57 offset:41408
	v_med3_i32 v57, v64, 32, v200
	v_lshl_add_u32 v57, v57, 2, v211
	ds_read_b32 v71, v57 offset:41344
	v_med3_i32 v57, v64, 48, v201
	v_lshl_add_u32 v57, v57, 2, v211
	ds_read_b32 v72, v57 offset:41280
	s_waitcnt lgkmcnt(7)
	v_add_f32_e32 v16, v16, v65
	v_exp_f32_e32 v65, v16
	s_waitcnt lgkmcnt(6)
	v_add_f32_e32 v16, v17, v66
	v_exp_f32_e32 v17, v16
	s_waitcnt lgkmcnt(5)
	v_add_f32_e32 v16, v18, v67
	s_waitcnt lgkmcnt(4)
	v_add_f32_e32 v18, v19, v68
	s_waitcnt lgkmcnt(3)
	v_add_f32_e32 v19, v20, v69
	s_waitcnt lgkmcnt(2)
	v_add_f32_e32 v20, v21, v70
	v_med3_i32 v59, v64, s94, v204
	v_exp_f32_e32 v66, v20
	s_waitcnt lgkmcnt(1)
	v_add_f32_e32 v20, v22, v71
	v_lshl_add_u32 v59, v59, 2, v211
	v_exp_f32_e32 v18, v18
	v_exp_f32_e32 v19, v19
	v_exp_f32_e32 v22, v20
	ds_read_b32 v59, v59 offset:40576
	v_exp_f32_e32 v16, v16
	s_waitcnt lgkmcnt(1)
	v_add_f32_e32 v20, v23, v72
	v_exp_f32_e32 v21, v20
	v_add_f32_e32 v20, v65, v17
	v_add_f32_e32 v17, v18, v19
	v_add_f32_e32 v19, v66, v22
	v_pk_add_f32 v[16:17], v[16:17], v[18:19]
	v_mul_f32_e32 v22, v48, v21
	v_pk_add_f32 v[16:17], v[20:21], v[16:17]
	ds_bpermute_b32 v20, v51, v22
	v_pk_mul_f32 v[18:19], v[48:49], v[16:17]
	ds_bpermute_b32 v18, v51, v18
	ds_bpermute_b32 v19, v51, v19
	v_med3_i32 v57, v64, s91, v202
	v_med3_i32 v58, v64, s89, v203
	v_med3_i32 v64, v64, s84, v209
	v_lshl_add_u32 v57, v57, 2, v211
	v_lshl_add_u32 v58, v58, 2, v211
	v_lshl_add_u32 v64, v64, 2, v211
	s_waitcnt lgkmcnt(0)
	v_pk_fma_f32 v[16:17], v[48:49], v[16:17], v[18:19]
	v_fmac_f32_e32 v20, v48, v21
	ds_read_b32 v57, v57 offset:40704
	ds_read_b32 v58, v58 offset:40640
	ds_read_b32 v64, v64 offset:40256
	ds_bpermute_b32 v18, v52, v16
	ds_bpermute_b32 v19, v52, v17
	ds_bpermute_b32 v22, v52, v20
	v_add_u32_e32 v56, s12, v152
	v_add_u32_e32 v21, s12, v54
	s_and_saveexec_b64 s[10:11], vcc
	s_cbranch_execz .LBB0_949
	s_waitcnt lgkmcnt(1)
	v_pk_add_f32 v[16:17], v[16:17], v[18:19]
	ds_read2_b32 v[18:19], v21 offset1:1
	v_cmp_gt_u32_e64 s[6:7], s34, v56
	s_waitcnt lgkmcnt(0)
	v_pk_add_f32 v[16:17], v[16:17], v[18:19]
	ds_write2_b32 v21, v16, v17 offset1:1
	s_and_b64 exec, exec, s[6:7]
	s_cbranch_execz .LBB0_949
	ds_read_b32 v17, v21 offset:8
	v_add_f32_e32 v16, v20, v22
	s_waitcnt lgkmcnt(0)
	v_add_f32_e32 v16, v16, v17
	ds_write_b32 v21, v16 offset:8

; #define LAS __attribute__((address_space(3)))
; __device__ __forceinline__ void imp_sub(f32x16& st, float invc, int nbase, LAS float* improw, int r) {
; #pragma unroll
;     for (int j = 0; j < 2; ++j) { const int a = (nbase + 16 * j) >> 3;
;         float s0 = ((st[8 * j] + st[8 * j + 1]) + (st[8 * j + 2] + st[8 * j + 3])) * invc;
;         float s1 = ((st[8 * j + 3] + st[8 * j + 4]) + (st[8 * j + 5] + st[8 * j + 6]) + st[8 * j + 7]) * invc;
;         float s2 = st[8 * j + 7] * invc;
;         s0 += __shfl_xor(s0, 8); s0 += __shfl_xor(s0, 16); s1 += __shfl_xor(s1, 8); s1 += __shfl_xor(s1, 16); s2 += __shfl_xor(s2, 8); s2 += __shfl_xor(s2, 16);
;         if (r < 8) { LAS float* ip = improw + 2 * a; ip[0] += s0; ip[1] += s1; if (2 * a + 2 < 128) ip[2] += s2; } }
; __device__ __forceinline__ void nsa_unit(LAS unsigned char* lds, const unsigned char* hb, const bf16_t* kc, const bf16_t* vct, const float* nsg, bf16_t* omix, int b, int g, int c, int tid) {
;     ...
;     TILE_LOOP(Kc, Vc, 512, 0, ntc, {
;         f32x16 s0 = qk_sub(ks, 0, qf, r, h); f32x16 s1 = qk_sub(ks, 1, qf, r, h); float dummy = 0.f;
;         const int dist00 = t - 31 - 16 * (key0 + 8 * h);
;         soft_sub<3>(s0, dummy, true, dist00, 0, bt); imp_sub(s0, invc, key0 + 8 * h, imp + ql * 129, r);
;         soft_sub<3>(s1, dummy, true, dist00 - 512, 0, bt); imp_sub(s1, invc, key0 + 32 + 8 * h, imp + ql * 129, r); });
.Lp2_join:
	s_cmp_ge_u32 s13, s17
	s_cbranch_scc1 .LBB0_943
	s_xor_b32 s6, s20, 1
	s_mulk_i32 s6, 0x4800
	v_add_u32_e32 v0, s6, v155
	s_waitcnt vmcnt(1)
	ds_write_b128 v0, v[36:39]
	s_waitcnt vmcnt(0)
	ds_write_b128 v0, v[32:35] offset:9216
	s_branch .LBB0_943
.Lp2_far:
	s_add_i32 s6, s13, -1
	s_and_b32 s20, s6, 1
	s_mul_i32 s6, s20, 0x4800
	v_add_u32_e32 v60, s6, v53
	ds_read_b128 v[0:3], v60
	ds_read_b128 v[4:7], v60 offset:32
	v_add_u32_e32 v64, 0x200, v55
	s_waitcnt lgkmcnt(1)
	v_mfma_f32_32x32x16_bf16 v[16:31], v[0:3], v[82:85], 0
	ds_read_b128 v[0:3], v60 offset:64
	ds_read_b128 v[56:59], v60 offset:4640
	ds_read_b32 v63, v211 offset:42620
	s_waitcnt lgkmcnt(3)
	v_mfma_f32_32x32x16_bf16 v[16:31], v[4:7], v[86:89], v[16:31]
	ds_read_b32 v62, v211 offset:42620
	ds_read_b32 v61, v211 offset:42620
	s_waitcnt lgkmcnt(4)
	v_mfma_f32_32x32x16_bf16 v[16:31], v[0:3], v[90:93], v[16:31]
	ds_read_b128 v[0:3], v60 offset:96
	s_waitcnt lgkmcnt(0)
	v_mfma_f32_32x32x16_bf16 v[16:31], v[0:3], v[94:97], v[16:31]
	ds_read_b128 v[0:3], v60 offset:4608
	s_waitcnt lgkmcnt(0)
	v_mfma_f32_32x32x16_bf16 v[0:15], v[0:3], v[82:85], 0
	v_mfma_f32_32x32x16_bf16 v[0:15], v[56:59], v[86:89], v[0:15]
	ds_read_b128 v[56:59], v60 offset:4672
	s_waitcnt lgkmcnt(0)
	v_mfma_f32_32x32x16_bf16 v[0:15], v[56:59], v[90:93], v[0:15]
	ds_read_b128 v[56:59], v60 offset:4704
	ds_read_b32 v60, v211 offset:42620
	s_waitcnt lgkmcnt(1)
	v_mfma_f32_32x32x16_bf16 v[0:15], v[56:59], v[94:97], v[0:15]
	ds_read_b32 v65, v211 offset:42620
	ds_read_b32 v66, v211 offset:42620
	ds_read_b32 v67, v211 offset:42620
	ds_read_b32 v68, v211 offset:42620
	ds_read_b32 v69, v211 offset:42620
	ds_read_b32 v70, v211 offset:42620
	ds_read_b32 v71, v211 offset:42620
	ds_read_b32 v72, v211 offset:42620
	s_waitcnt lgkmcnt(7)
	v_add_f32_e32 v16, v16, v65
	v_exp_f32_e32 v65, v16
	s_waitcnt lgkmcnt(6)
	v_add_f32_e32 v16, v17, v66
	v_exp_f32_e32 v17, v16
	s_waitcnt lgkmcnt(5)
	v_add_f32_e32 v16, v18, v67
	s_waitcnt lgkmcnt(4)
	v_add_f32_e32 v18, v19, v68
	s_waitcnt lgkmcnt(3)
	v_add_f32_e32 v19, v20, v69
	s_waitcnt lgkmcnt(2)
	v_add_f32_e32 v20, v21, v70
	v_exp_f32_e32 v66, v20
	s_waitcnt lgkmcnt(1)
	v_add_f32_e32 v20, v22, v71
	v_exp_f32_e32 v18, v18
	v_exp_f32_e32 v19, v19
	v_exp_f32_e32 v22, v20
	ds_read_b32 v59, v211 offset:42620
	v_exp_f32_e32 v16, v16
	s_waitcnt lgkmcnt(1)
	v_add_f32_e32 v20, v23, v72
	v_exp_f32_e32 v21, v20
	v_add_f32_e32 v20, v65, v17
	v_add_f32_e32 v17, v18, v19
	v_add_f32_e32 v19, v66, v22
	v_pk_add_f32 v[16:17], v[16:17], v[18:19]
	v_mul_f32_e32 v22, v48, v21
	v_pk_add_f32 v[16:17], v[20:21], v[16:17]
	ds_bpermute_b32 v20, v51, v22
	v_pk_mul_f32 v[18:19], v[48:49], v[16:17]
	ds_bpermute_b32 v18, v51, v18
	ds_bpermute_b32 v19, v51, v19
	s_waitcnt lgkmcnt(0)
	v_pk_fma_f32 v[16:17], v[48:49], v[16:17], v[18:19]
	v_fmac_f32_e32 v20, v48, v21
	ds_read_b32 v57, v211 offset:42620
	ds_read_b32 v58, v211 offset:42620
	ds_read_b32 v64, v211 offset:42620
	ds_bpermute_b32 v18, v52, v16
	ds_bpermute_b32 v19, v52, v17
	ds_bpermute_b32 v22, v52, v20
	v_add_u32_e32 v56, s12, v152
	v_add_u32_e32 v21, s12, v54
	s_and_saveexec_b64 s[10:11], vcc
	s_cbranch_execz .Lp2f_949
	s_waitcnt lgkmcnt(1)
	v_pk_add_f32 v[16:17], v[16:17], v[18:19]
	ds_read2_b32 v[18:19], v21 offset1:1
	v_cmp_gt_u32_e64 s[6:7], s34, v56
	s_waitcnt lgkmcnt(0)
	v_pk_add_f32 v[16:17], v[16:17], v[18:19]
	ds_write2_b32 v21, v16, v17 offset1:1
	s_and_b64 exec, exec, s[6:7]
	s_cbranch_execz .Lp2f_949
	ds_read_b32 v17, v21 offset:8
	v_add_f32_e32 v16, v20, v22
	s_waitcnt lgkmcnt(0)
	v_add_f32_e32 v16, v16, v17
	ds_write_b32 v21, v16 offset:8

; #define LAS __attribute__((address_space(3)))
; __device__ __forceinline__ void imp_sub(f32x16& st, float invc, int nbase, LAS float* improw, int r) {
; #pragma unroll
;     for (int j = 0; j < 2; ++j) { const int a = (nbase + 16 * j) >> 3;
;         float s0 = ((st[8 * j] + st[8 * j + 1]) + (st[8 * j + 2] + st[8 * j + 3])) * invc;
;         float s1 = ((st[8 * j + 3] + st[8 * j + 4]) + (st[8 * j + 5] + st[8 * j + 6]) + st[8 * j + 7]) * invc;
;         float s2 = st[8 * j + 7] * invc;
;         s0 += __shfl_xor(s0, 8); s0 += __shfl_xor(s0, 16); s1 += __shfl_xor(s1, 8); s1 += __shfl_xor(s1, 16); s2 += __shfl_xor(s2, 8); s2 += __shfl_xor(s2, 16);
;         if (r < 8) { LAS float* ip = improw + 2 * a; ip[0] += s0; ip[1] += s1; if (2 * a + 2 < 128) ip[2] += s2; } }
; __device__ __forceinline__ void nsa_unit(LAS unsigned char* lds, const unsigned char* hb, const bf16_t* kc, const bf16_t* vct, const float* nsg, bf16_t* omix, int b, int g, int c, int tid) {
;     ...
;         soft_sub<3>(s0, dummy, true, dist00, 0, bt); imp_sub(s0, invc, key0 + 8 * h, imp + ql * 129, r);
;         soft_sub<3>(s1, dummy, true, dist00 - 512, 0, bt); imp_sub(s1, invc, key0 + 32 + 8 * h, imp + ql * 129, r); });
.Lp2f_952:
	s_or_b64 exec, exec, s[10:11]
	s_waitcnt lgkmcnt(1)
	s_waitcnt lgkmcnt(0)
	ds_read_b32 v16, v211 offset:42620
	ds_read_b32 v17, v211 offset:42620
	ds_read_b32 v18, v211 offset:42620
	ds_read_b32 v19, v211 offset:42620
	ds_read_b32 v23, v211 offset:42620
	ds_read_b32 v24, v211 offset:42620
	ds_read_b32 v25, v211 offset:42620
	ds_read_b32 v26, v211 offset:42620
	s_waitcnt lgkmcnt(7)
	v_add_f32_e32 v0, v0, v16
	v_exp_f32_e32 v16, v0
	s_waitcnt lgkmcnt(6)
	v_add_f32_e32 v0, v1, v17
	v_exp_f32_e32 v1, v0
	s_waitcnt lgkmcnt(5)
	v_add_f32_e32 v0, v2, v18
	s_waitcnt lgkmcnt(4)
	v_add_f32_e32 v2, v3, v19
	s_waitcnt lgkmcnt(3)
	v_add_f32_e32 v3, v4, v23
	s_waitcnt lgkmcnt(2)
	v_add_f32_e32 v4, v5, v24
	s_waitcnt lgkmcnt(1)
	v_add_f32_e32 v5, v6, v25
	v_exp_f32_e32 v2, v2
	v_exp_f32_e32 v3, v3
	v_exp_f32_e32 v4, v4
	v_exp_f32_e32 v5, v5
	v_exp_f32_e32 v0, v0
	s_waitcnt lgkmcnt(0)
	v_add_f32_e32 v6, v7, v26
	v_exp_f32_e32 v25, v6
	v_add_f32_e32 v24, v16, v1
	v_add_f32_e32 v1, v2, v3
	v_add_f32_e32 v3, v4, v5
	v_pk_add_f32 v[0:1], v[0:1], v[2:3]
	v_pk_add_f32 v[0:1], v[24:25], v[0:1]
	v_mul_f32_e32 v4, v48, v25
	v_pk_mul_f32 v[2:3], v[48:49], v[0:1]
	ds_bpermute_b32 v2, v51, v2
	ds_bpermute_b32 v3, v51, v3
	ds_bpermute_b32 v23, v51, v4
	ds_read_b32 v19, v211 offset:42620
	ds_read_b32 v18, v211 offset:42620
	ds_read_b32 v17, v211 offset:42620
	ds_read_b32 v16, v211 offset:42620
	ds_read_b32 v7, v211 offset:42620
	ds_read_b32 v6, v211 offset:42620
	ds_read_b32 v5, v211 offset:42620
	ds_read_b32 v4, v211 offset:42620
	s_waitcnt lgkmcnt(9)
	v_pk_fma_f32 v[0:1], v[48:49], v[0:1], v[2:3]
	s_waitcnt lgkmcnt(8)
	v_fmac_f32_e32 v23, v48, v25
	ds_bpermute_b32 v2, v52, v0
	ds_bpermute_b32 v3, v52, v1
	ds_bpermute_b32 v24, v52, v23
	s_and_saveexec_b64 s[10:11], vcc
	s_cbranch_execz .Lp2f_955
	s_waitcnt lgkmcnt(1)
	v_pk_add_f32 v[0:1], v[0:1], v[2:3]
	ds_read2_b32 v[2:3], v21 offset0:8 offset1:9
	v_add_u32_e32 v25, 32, v56
	v_cmp_gt_u32_e64 s[6:7], s34, v25
	s_waitcnt lgkmcnt(0)
	v_pk_add_f32 v[0:1], v[0:1], v[2:3]
	ds_write2_b32 v21, v0, v1 offset0:8 offset1:9
	s_and_b64 exec, exec, s[6:7]
	s_cbranch_execz .Lp2f_955
	ds_read_b32 v1, v21 offset:40
	v_add_f32_e32 v0, v23, v24
	s_waitcnt lgkmcnt(0)
	v_add_f32_e32 v0, v0, v1
	ds_write_b32 v21, v0 offset:40

; __device__ __forceinline__ void nsa_unit(LAS unsigned char* lds, const unsigned char* hb, const bf16_t* kc, const bf16_t* vct, const float* nsg, bf16_t* omix, int b, int g, int c, int tid) {
;     ...
;     TILE_LOOP(Kc, Vc, 512, 0, ntc, {
;         f32x16 s0 = qk_sub(ks, 0, qf, r, h); f32x16 s1 = qk_sub(ks, 1, qf, r, h); float dummy = 0.f;
;         const int dist00 = t - 31 - 16 * (key0 + 8 * h);
;         soft_sub<3>(s0, dummy, true, dist00, 0, bt); imp_sub(s0, invc, key0 + 8 * h, imp + ql * 129, r);
;         soft_sub<3>(s1, dummy, true, dist00 - 512, 0, bt); imp_sub(s1, invc, key0 + 32 + 8 * h, imp + ql * 129, r); });
.Lp2f_958:
	s_or_b64 exec, exec, s[10:11]
	s_branch .Lp2_join

; __global__ void __launch_bounds__(512, 2) hybrid_fwd(Params P) {
;     ...
;         { PHASE_BEGIN
;             for (int it = bx; it < 256; it += G)
;                 for (int i = 0; i < 4; ++i) { int tidu = tid; asm volatile("" : "+v"(tidu));
;                     branch_tile(lds, (const bf16_t*)(ws + WS_H), (const bf16_t*)(ws + WS_WBR), (const bf16_t*)(ws + WS_A), (bf16_t*)(ws + WS_B), it >> 1, 4 * (it & 1) + i, tidu); }
.LBB0_1085:
	s_nop 0
	s_nop 0
	s_nop 0
	s_nop 0
	s_nop 0
	s_nop 0
	s_nop 0
	s_nop 0
	s_nop 0
	s_nop 0
	s_nop 0
	s_or_b64 exec, exec, s[4:5]
	s_mov_b32 s4, s34
	s_barrier
	s_mov_b64 s[4:5], s[58:59]
	s_mov_b32 s16, s69
	s_mov_b32 s17, s2
	v_mov_b32_e32 v138, v146
	s_cmpk_gt_i32 s17, 0xff
	s_cbranch_scc1 .LBB0_1096
	s_add_u32 s18, s4, 0x3100000
	s_addc_u32 s19, s5, 0
	s_add_u32 s20, s4, 0xd00000
	s_addc_u32 s21, s5, 0
	s_add_u32 s6, s4, 0x7100000
	s_addc_u32 s7, s5, 0
	s_add_u32 s8, s4, 0x13100000
	s_addc_u32 s9, s5, 0
	s_branch .LBB0_1088
